# latent attention PV: V fragment reads three fragments ahead, without filler wait states
# baseline (speedup 1.0000x reference)
.LBB0_140:
	ds_read_b64_tr_b16 v[68:69], v242 offset:9216
	ds_read_b64_tr_b16 v[70:71], v242 offset:10368
	ds_read_b64_tr_b16 v[72:73], v242 offset:9280
	ds_read_b64_tr_b16 v[74:75], v242 offset:10432
	ds_read_b64_tr_b16 v[76:77], v242 offset:11520
	ds_read_b64_tr_b16 v[78:79], v242 offset:12672
	v_sub_f32_e32 v48, v172, v1
	v_exp_f32_e32 v51, v48
	v_sub_f32_e32 v49, v173, v1
	v_exp_f32_e32 v52, v49
	v_sub_f32_e32 v14, v14, v1
	v_exp_f32_e32 v53, v14
	v_sub_f32_e32 v15, v15, v1
	v_exp_f32_e32 v56, v15
	v_sub_f32_e32 v10, v10, v1
	v_add_f32_e32 v48, 0, v51
	v_exp_f32_e32 v54, v10
	v_sub_f32_e32 v11, v11, v1
	v_add_f32_e32 v48, v52, v48
	v_exp_f32_e32 v57, v11
	v_sub_f32_e32 v11, v12, v1
	v_add_f32_e32 v14, v53, v48
	v_exp_f32_e32 v55, v11
	v_sub_f32_e32 v11, v13, v1
	v_add_f32_e32 v14, v56, v14
	v_exp_f32_e32 v58, v11
	v_add_f32_e32 v10, v54, v14
	v_add_f32_e32 v10, v57, v10
	v_add_f32_e32 v10, v55, v10
	v_add_f32_e32 v10, v58, v10
	v_cvt_pk_bf16_f32 v55, v55, v58
	v_cvt_pk_bf16_f32 v54, v54, v57
	v_cvt_pk_bf16_f32 v53, v53, v56
	v_sub_f32_e32 v3, v3, v1
	v_exp_f32_e32 v61, v3
	v_sub_f32_e32 v3, v4, v1
	v_cvt_pk_bf16_f32 v52, v51, v52
	v_exp_f32_e32 v62, v3
	v_sub_f32_e32 v3, v5, v1
	s_waitcnt lgkmcnt(4)
	v_mfma_f32_32x32x16_bf16 v[32:47], v[68:71], v[52:55], v[32:47]
	ds_read_b64_tr_b16 v[68:69], v242 offset:11584
	ds_read_b64_tr_b16 v[70:71], v242 offset:12736
	v_exp_f32_e32 v63, v3
	v_sub_f32_e32 v3, v6, v1
	v_exp_f32_e32 v64, v3
	v_sub_f32_e32 v3, v7, v1
	v_exp_f32_e32 v65, v3
	v_sub_f32_e32 v3, v8, v1
	v_sub_f32_e32 v2, v2, v1
	v_exp_f32_e32 v66, v3
	v_sub_f32_e32 v3, v9, v1
	v_exp_f32_e32 v60, v2
	v_exp_f32_e32 v67, v3
	s_waitcnt lgkmcnt(4)
	v_mfma_f32_32x32x16_bf16 v[16:31], v[72:75], v[52:55], v[16:31]
	ds_read_b64_tr_b16 v[72:73], v242 offset:13824
	ds_read_b64_tr_b16 v[74:75], v242 offset:14976
	v_cvt_pk_bf16_f32 v54, v64, v65
	v_cvt_pk_bf16_f32 v55, v66, v67
	v_cvt_pk_bf16_f32 v53, v62, v63
	v_cvt_pk_bf16_f32 v52, v60, v61
	v_add_f32_e32 v2, v60, v10
	v_sub_f32_e32 v3, v174, v1
	s_waitcnt lgkmcnt(4)
	v_mfma_f32_32x32x16_bf16 v[32:47], v[76:79], v[52:55], v[32:47]
	ds_read_b64_tr_b16 v[76:77], v242 offset:13888
	ds_read_b64_tr_b16 v[78:79], v242 offset:15040
	v_sub_f32_e32 v4, v175, v1
	v_sub_f32_e32 v5, v176, v1
	v_sub_f32_e32 v6, v177, v1
	v_sub_f32_e32 v7, v178, v1
	v_sub_f32_e32 v8, v179, v1
	v_sub_f32_e32 v9, v180, v1
	v_sub_f32_e32 v10, v181, v1
	v_exp_f32_e32 v3, v3
	v_exp_f32_e32 v4, v4
	v_exp_f32_e32 v5, v5
	v_exp_f32_e32 v6, v6
	v_exp_f32_e32 v7, v7
	v_exp_f32_e32 v8, v8
	v_exp_f32_e32 v9, v9
	v_exp_f32_e32 v10, v10
	s_waitcnt lgkmcnt(4)
	v_mfma_f32_32x32x16_bf16 v[16:31], v[68:71], v[52:55], v[16:31]
	ds_read_b64_tr_b16 v[68:69], v242 offset:16128
	ds_read_b64_tr_b16 v[70:71], v242 offset:17280
	v_add_f32_e32 v2, v61, v2
	v_cvt_pk_bf16_f32 v55, v9, v10
	v_cvt_pk_bf16_f32 v54, v7, v8
	v_cvt_pk_bf16_f32 v53, v5, v6
	v_cvt_pk_bf16_f32 v52, v3, v4
	v_add_f32_e32 v2, v62, v2
	v_add_f32_e32 v2, v63, v2
	s_waitcnt lgkmcnt(4)
	v_mfma_f32_32x32x16_bf16 v[32:47], v[72:75], v[52:55], v[32:47]
	ds_read_b64_tr_b16 v[72:73], v242 offset:16192
	ds_read_b64_tr_b16 v[74:75], v242 offset:17344
	v_add_f32_e32 v2, v64, v2
	v_add_f32_e32 v2, v65, v2
	v_add_f32_e32 v2, v66, v2
	v_sub_f32_e32 v11, v182, v1
	v_sub_f32_e32 v12, v183, v1
	v_sub_f32_e32 v13, v184, v1
	v_sub_f32_e32 v14, v185, v1
	v_sub_f32_e32 v15, v186, v1
	v_sub_f32_e32 v48, v187, v1
	v_sub_f32_e32 v49, v188, v1
	v_sub_f32_e32 v50, v189, v1
	v_add_f32_e32 v2, v67, v2
	v_exp_f32_e32 v11, v11
	v_exp_f32_e32 v12, v12
	v_exp_f32_e32 v13, v13
	v_exp_f32_e32 v14, v14
	v_exp_f32_e32 v15, v15
	v_exp_f32_e32 v48, v48
	v_exp_f32_e32 v49, v49
	v_exp_f32_e32 v50, v50
	s_waitcnt lgkmcnt(4)
	v_mfma_f32_32x32x16_bf16 v[16:31], v[76:79], v[52:55], v[16:31]
	v_add_f32_e32 v2, v3, v2
	v_add_f32_e32 v2, v4, v2
	v_add_f32_e32 v2, v5, v2
	v_cvt_pk_bf16_f32 v55, v49, v50
	v_cvt_pk_bf16_f32 v54, v15, v48
	v_cvt_pk_bf16_f32 v53, v13, v14
	v_cvt_pk_bf16_f32 v52, v11, v12
	v_add_f32_e32 v2, v6, v2
	v_add_f32_e32 v2, v7, v2
	s_waitcnt lgkmcnt(2)
	v_mfma_f32_32x32x16_bf16 v[32:47], v[68:71], v[52:55], v[32:47]
	v_add_f32_e32 v2, v8, v2
	v_add_f32_e32 v2, v9, v2
	v_add_f32_e32 v2, v10, v2
	v_add_f32_e32 v2, v11, v2
	v_add_f32_e32 v2, v12, v2
	v_add_f32_e32 v2, v13, v2
	s_waitcnt lgkmcnt(0)
	v_mfma_f32_32x32x16_bf16 v[16:31], v[72:75], v[52:55], v[16:31]
	v_add_f32_e32 v2, v14, v2
	v_add_f32_e32 v2, v15, v2
	v_add_f32_e32 v2, v48, v2
	v_add_f32_e32 v2, v49, v2
	v_add_f32_e32 v2, v50, v2
	v_add_f32_e32 v243, v2, v243
	v_mov_b32_e32 v244, v1
